# v31 + grid-barrier spin loops poll with s_sleep 8
# baseline (speedup 1.0000x reference)
.LBB0_1308:
	s_and_b32 s18, s40, 0xff
	s_mov_b64 s[16:17], -1
	s_cmp_lg_u32 s18, 0
	s_mov_b64 s[38:39], -1
	s_sleep 8
	s_cbranch_scc1 .LBB0_1311
	v_readlane_b32 s18, v251, 45
	v_readlane_b32 s19, v251, 46
	s_nop 4
	global_load_dword v2, v1, s[18:19] sc1
	s_waitcnt vmcnt(0)
	v_cmp_eq_u32_e32 vcc, 0, v2
	s_cbranch_vccnz .LBB0_1313
	s_mov_b64 s[38:39], 0
	s_mov_b64 s[18:19], -1
